# speedup vs baseline: 1.0413x; 1.0413x over previous
; DEV void gemm_tile(const u16* __restrict__ A, const u16* __restrict__ Bt, u16* __restrict__ C, int N, int K,
;                    int brow, int bcol, unsigned char* smem, int epi, const GateEpi& ge) {
;     ...
;   u16* Cw = C + (size_t)(brow + wr * 64) * N + bcol + wc * 32;
; #pragma unroll
;   for (int ai = 0; ai < 2; ++ai)
; #pragma unroll
;     for (int bj = 0; bj < 2; ++bj)
; #pragma unroll
;       for (int m = 0; m < 4; ++m)
; #pragma unroll
;         for (int n = 0; n < 2; ++n)
; #pragma unroll
;           for (int j = 0; j < 4; ++j)
;             Cw[(size_t)(ai * 128 + m * 16 + fq2 * 4 + j) * N + (bj * 128 + n * 16 + fr2)] = f2bf(acc[ai][bj][m][n][j]);
.Lg_epi:
	v_readfirstlane_b32 s0, v160
	s_andn2_b32 s0, s0, 63
	s_andn2_b64 vcc, exec, s[2:3]
	v_or_b32_e32 v180, s0, v161
	s_nop 0
	v_bfe_u32 v181, v180, 4, 2
	v_and_b32_e32 v180, 15, v180
	s_cbranch_vccz .Lg_gate
	s_add_i32 s0, s51, s49
	s_mul_hi_u32 s1, s0, s44
	s_mul_i32 s0, s0, s44
	s_lshl_b64 s[0:1], s[0:1], 1
	s_add_u32 s0, s14, s0
	s_addc_u32 s1, s15, s1
	s_lshl_b64 s[4:5], s[92:93], 1
	s_add_u32 s0, s0, s4
	s_addc_u32 s1, s1, s5
	s_lshl_b32 s4, s50, 6
	s_add_u32 s0, s0, s4
	s_addc_u32 s1, s1, 0
	v_mul_u32_u24_e32 v153, s44, v180
	v_lshlrev_b32_e32 v153, 1, v153
	v_lshl_add_u32 v153, v181, 4, v153
	s_lshl_b32 s4, s44, 5
	s_lshl_b32 s5, s44, 7
	v_cvt_pk_bf16_f32 v184, v124, v125
	v_cvt_pk_bf16_f32 v185, v126, v127
	v_cvt_pk_bf16_f32 v186, v120, v121
	v_cvt_pk_bf16_f32 v187, v122, v123
	global_store_dwordx4 v153, v[184:187], s[0:1]
	global_store_dwordx4 v153, v[184:187], s[0:1]
	v_cvt_pk_bf16_f32 v188, v84, v85
	v_cvt_pk_bf16_f32 v189, v86, v87
	v_cvt_pk_bf16_f32 v190, v68, v69
	v_cvt_pk_bf16_f32 v191, v70, v71
	global_store_dwordx4 v153, v[188:191], s[0:1] offset:256
	global_store_dwordx4 v153, v[188:191], s[0:1] offset:256
	s_add_u32 s0, s0, s4
	s_addc_u32 s1, s1, 0
	v_cvt_pk_bf16_f32 v192, v116, v117
	v_cvt_pk_bf16_f32 v193, v118, v119
	v_cvt_pk_bf16_f32 v194, v112, v113
	v_cvt_pk_bf16_f32 v195, v114, v115
	global_store_dwordx4 v153, v[192:195], s[0:1]
	global_store_dwordx4 v153, v[192:195], s[0:1]
	v_cvt_pk_bf16_f32 v196, v52, v53
	v_cvt_pk_bf16_f32 v197, v54, v55
	v_cvt_pk_bf16_f32 v198, v48, v49
	v_cvt_pk_bf16_f32 v199, v50, v51
	global_store_dwordx4 v153, v[196:199], s[0:1] offset:256
	global_store_dwordx4 v153, v[196:199], s[0:1] offset:256
	s_add_u32 s0, s0, s4
	s_addc_u32 s1, s1, 0
	v_cvt_pk_bf16_f32 v184, v108, v109
	v_cvt_pk_bf16_f32 v185, v110, v111
	v_cvt_pk_bf16_f32 v186, v104, v105
	v_cvt_pk_bf16_f32 v187, v106, v107
	global_store_dwordx4 v153, v[184:187], s[0:1]
	global_store_dwordx4 v153, v[184:187], s[0:1]
	v_cvt_pk_bf16_f32 v188, v44, v45
	v_cvt_pk_bf16_f32 v189, v46, v47
	v_cvt_pk_bf16_f32 v190, v40, v41
	v_cvt_pk_bf16_f32 v191, v42, v43
	global_store_dwordx4 v153, v[188:191], s[0:1] offset:256
	global_store_dwordx4 v153, v[188:191], s[0:1] offset:256
	s_add_u32 s0, s0, s4
	s_addc_u32 s1, s1, 0
	v_cvt_pk_bf16_f32 v192, v100, v101
	v_cvt_pk_bf16_f32 v193, v102, v103
	v_cvt_pk_bf16_f32 v194, v96, v97
	v_cvt_pk_bf16_f32 v195, v98, v99
	global_store_dwordx4 v153, v[192:195], s[0:1]
	global_store_dwordx4 v153, v[192:195], s[0:1]
	v_cvt_pk_bf16_f32 v196, v36, v37
	v_cvt_pk_bf16_f32 v197, v38, v39
	v_cvt_pk_bf16_f32 v198, v32, v33
	v_cvt_pk_bf16_f32 v199, v34, v35
	global_store_dwordx4 v153, v[196:199], s[0:1] offset:256
	global_store_dwordx4 v153, v[196:199], s[0:1] offset:256
	s_add_u32 s0, s0, s4
	s_addc_u32 s1, s1, 0
	s_add_u32 s0, s0, s5
	s_addc_u32 s1, s1, 0
	v_cvt_pk_bf16_f32 v184, v28, v29
	v_cvt_pk_bf16_f32 v185, v30, v31
	v_cvt_pk_bf16_f32 v186, v24, v25
	v_cvt_pk_bf16_f32 v187, v26, v27
	global_store_dwordx4 v153, v[184:187], s[0:1]
	global_store_dwordx4 v153, v[184:187], s[0:1]
	v_cvt_pk_bf16_f32 v188, v56, v57
	v_cvt_pk_bf16_f32 v189, v58, v59
	v_cvt_pk_bf16_f32 v190, v60, v61
	v_cvt_pk_bf16_f32 v191, v62, v63
	global_store_dwordx4 v153, v[188:191], s[0:1] offset:256
	global_store_dwordx4 v153, v[188:191], s[0:1] offset:256
	s_add_u32 s0, s0, s4
	s_addc_u32 s1, s1, 0
	v_cvt_pk_bf16_f32 v192, v20, v21
	v_cvt_pk_bf16_f32 v193, v22, v23
	v_cvt_pk_bf16_f32 v194, v16, v17
	v_cvt_pk_bf16_f32 v195, v18, v19
	global_store_dwordx4 v153, v[192:195], s[0:1]
	global_store_dwordx4 v153, v[192:195], s[0:1]
	v_cvt_pk_bf16_f32 v196, v64, v65
	v_cvt_pk_bf16_f32 v197, v66, v67
	v_cvt_pk_bf16_f32 v198, v72, v73
	v_cvt_pk_bf16_f32 v199, v74, v75
	global_store_dwordx4 v153, v[196:199], s[0:1] offset:256
	global_store_dwordx4 v153, v[196:199], s[0:1] offset:256
	s_add_u32 s0, s0, s4
	s_addc_u32 s1, s1, 0
	v_cvt_pk_bf16_f32 v184, v12, v13
	v_cvt_pk_bf16_f32 v185, v14, v15
	v_cvt_pk_bf16_f32 v186, v8, v9
	v_cvt_pk_bf16_f32 v187, v10, v11
	global_store_dwordx4 v153, v[184:187], s[0:1]
	global_store_dwordx4 v153, v[184:187], s[0:1]
	v_cvt_pk_bf16_f32 v188, v76, v77
	v_cvt_pk_bf16_f32 v189, v78, v79
	v_cvt_pk_bf16_f32 v190, v80, v81
	v_cvt_pk_bf16_f32 v191, v82, v83
	global_store_dwordx4 v153, v[188:191], s[0:1] offset:256
	global_store_dwordx4 v153, v[188:191], s[0:1] offset:256
	s_add_u32 s0, s0, s4
	s_addc_u32 s1, s1, 0
	v_cvt_pk_bf16_f32 v192, v4, v5
	v_cvt_pk_bf16_f32 v193, v6, v7
	v_cvt_pk_bf16_f32 v194, v0, v1
	v_cvt_pk_bf16_f32 v195, v2, v3
	global_store_dwordx4 v153, v[192:195], s[0:1]
	global_store_dwordx4 v153, v[192:195], s[0:1]
	v_cvt_pk_bf16_f32 v196, v88, v89
	v_cvt_pk_bf16_f32 v197, v90, v91
	v_cvt_pk_bf16_f32 v198, v92, v93
	v_cvt_pk_bf16_f32 v199, v94, v95
	global_store_dwordx4 v153, v[196:199], s[0:1] offset:256
	global_store_dwordx4 v153, v[196:199], s[0:1] offset:256
	s_branch .Lg_post
